# v117 + scan: SrcC ds_read2 issued before the next group's fragment prefetch reads, lgkmcnt(0) -> lgkmcnt(4) at three sites
# baseline (speedup 1.0000x reference)
.Lscan_noload:
	s_waitcnt lgkmcnt(7)
	v_mfma_f32_16x16x32_bf16 v[152:155], v[152:155], v[94:97], 0
	s_waitcnt lgkmcnt(6)
	v_mfma_f32_16x16x32_bf16 v[152:155], v[170:173], v[98:101], v[152:155]
	s_waitcnt lgkmcnt(5)
	v_mfma_f32_16x16x32_bf16 v[152:155], v[174:177], v[102:105], v[152:155]
	s_waitcnt lgkmcnt(4)
	v_mfma_f32_16x16x32_bf16 v[152:155], v[178:181], v[106:109], v[152:155]
	ds_read_b128 v[170:173], v164 offset:30464
	ds_read_b128 v[174:177], v164 offset:30528
	ds_read_b128 v[178:181], v164 offset:30592
	ds_read_b128 v[186:189], v164 offset:30656
	s_waitcnt lgkmcnt(7)
	v_mfma_f32_16x16x32_bf16 v[114:117], v[114:117], v[94:97], 0
	s_waitcnt lgkmcnt(6)
	v_mfma_f32_16x16x32_bf16 v[114:117], v[144:147], v[98:101], v[114:117]
	s_waitcnt lgkmcnt(5)
	v_mfma_f32_16x16x32_bf16 v[114:117], v[148:151], v[102:105], v[114:117]
	s_waitcnt lgkmcnt(4)
	v_mfma_f32_16x16x32_bf16 v[114:117], v[182:185], v[106:109], v[114:117]
	ds_read_b128 v[144:147], v164
	ds_read_b128 v[148:151], v164 offset:64
	ds_read_b128 v[182:185], v164 offset:128
	ds_read_b128 v[190:193], v164 offset:192
	s_waitcnt lgkmcnt(7)
	v_mfma_f32_16x16x32_bf16 v[170:173], v[170:173], v[94:97], 0
	s_waitcnt lgkmcnt(6)
	v_mfma_f32_16x16x32_bf16 v[170:173], v[174:177], v[98:101], v[170:173]
	s_waitcnt lgkmcnt(5)
	v_mfma_f32_16x16x32_bf16 v[170:173], v[178:181], v[102:105], v[170:173]
	s_waitcnt lgkmcnt(4)
	v_mfma_f32_16x16x32_bf16 v[170:173], v[186:189], v[106:109], v[170:173]
	v_add_u32_e32 v142, 0x400, v163
	ds_read2_b32 v[198:199], v163 offset1:132
	ds_read2_b32 v[200:201], v142 offset0:8 offset1:140
	ds_read_b128 v[174:177], v164 offset:4352
	ds_read_b128 v[178:181], v164 offset:4416
	ds_read_b128 v[186:189], v164 offset:4480
	ds_read_b128 v[194:197], v164 offset:4544
	s_waitcnt lgkmcnt(4)
	v_mfma_f32_16x16x32_bf16 v[144:147], v[144:147], v[94:97], v[198:201]
	v_mfma_f32_16x16x32_bf16 v[144:147], v[148:151], v[98:101], v[144:147]
	v_mfma_f32_16x16x32_bf16 v[144:147], v[182:185], v[102:105], v[144:147]
	v_mfma_f32_16x16x32_bf16 v[144:147], v[190:193], v[106:109], v[144:147]
	v_add_u32_e32 v142, 0x2000, v163
	ds_read2_b32 v[202:203], v142 offset0:64 offset1:196
	v_add_u32_e32 v142, 0x2400, v163
	ds_read2_b32 v[204:205], v142 offset0:72 offset1:204
	ds_read_b128 v[148:151], v164 offset:8704
	ds_read_b128 v[182:185], v164 offset:8768
	ds_read_b128 v[190:193], v164 offset:8832
	ds_read_b128 v[198:201], v164 offset:8896
	s_waitcnt lgkmcnt(4)
	v_mfma_f32_16x16x32_bf16 v[174:177], v[174:177], v[94:97], v[202:205]
	v_mfma_f32_16x16x32_bf16 v[174:177], v[178:181], v[98:101], v[174:177]
	v_mfma_f32_16x16x32_bf16 v[174:177], v[186:189], v[102:105], v[174:177]
	v_mfma_f32_16x16x32_bf16 v[174:177], v[194:197], v[106:109], v[174:177]
	v_add_u32_e32 v142, 0x4200, v163
	ds_read2_b32 v[206:207], v142 offset1:132
	v_add_u32_e32 v142, 0x4600, v163
	ds_read2_b32 v[208:209], v142 offset0:8 offset1:140
	ds_read_b128 v[178:181], v164 offset:13056
	ds_read_b128 v[186:189], v164 offset:13120
	ds_read_b128 v[194:197], v164 offset:13184
	ds_read_b128 v[202:205], v164 offset:13248
	s_waitcnt lgkmcnt(4)
	v_mfma_f32_16x16x32_bf16 v[148:151], v[148:151], v[94:97], v[206:209]
	v_mfma_f32_16x16x32_bf16 v[148:151], v[182:185], v[98:101], v[148:151]
	v_mfma_f32_16x16x32_bf16 v[148:151], v[190:193], v[102:105], v[148:151]
	v_mfma_f32_16x16x32_bf16 v[148:151], v[198:201], v[106:109], v[148:151]
	ds_read_b128 v[182:185], v165 offset:34816
	ds_read_b128 v[190:193], v165 offset:34880
	ds_read_b128 v[198:201], v165 offset:37120
	ds_read_b128 v[206:209], v165 offset:37184
	v_add_u32_e32 v142, 0x6200, v163
	ds_read2_b32 v[210:211], v142 offset0:64 offset1:196
	v_add_u32_e32 v142, 0x6600, v163
	ds_read2_b32 v[212:213], v142 offset0:72 offset1:204
	s_waitcnt lgkmcnt(0)
	v_mfma_f32_16x16x32_bf16 v[94:97], v[178:181], v[94:97], v[210:213]
	v_mfma_f32_16x16x32_bf16 v[94:97], v[186:189], v[98:101], v[94:97]
	v_mfma_f32_16x16x32_bf16 v[94:97], v[194:197], v[102:105], v[94:97]
	ds_read_b128 v[98:101], v165 offset:39424
	ds_read_b128 v[102:105], v165 offset:39488
	ds_read_b128 v[178:181], v165 offset:41728
	ds_read_b128 v[186:189], v165 offset:41792
	v_mfma_f32_16x16x32_bf16 v[94:97], v[202:205], v[106:109], v[94:97]
	v_cvt_pk_bf16_f32 v106, v144, v145
	v_cvt_pk_bf16_f32 v107, v146, v147
	v_cvt_pk_bf16_f32 v108, v174, v175
	v_cvt_pk_bf16_f32 v109, v176, v177
	v_cvt_pk_bf16_f32 v144, v148, v149
	v_cvt_pk_bf16_f32 v145, v150, v151
	v_mfma_f32_16x16x32_bf16 v[110:113], v[182:185], v[106:109], v[110:113]
	s_nop 0
	v_cvt_pk_bf16_f32 v146, v94, v95
	v_cvt_pk_bf16_f32 v147, v96, v97
	s_nop 1
	v_mfma_f32_16x16x32_bf16 v[94:97], v[190:193], v[144:147], v[110:113]
	v_mfma_f32_16x16x32_bf16 v[110:113], v[198:201], v[106:109], v[152:155]
	ds_read_b128 v[148:151], v165 offset:44032
	s_nop 1
	ds_read_b128 v[152:155], v165 offset:44096
	ds_read_b128 v[174:177], v165 offset:46336
	ds_read_b128 v[182:185], v165 offset:46400
	v_mfma_f32_16x16x32_bf16 v[110:113], v[206:209], v[144:147], v[110:113]
	s_waitcnt lgkmcnt(7)
	v_mfma_f32_16x16x32_bf16 v[98:101], v[98:101], v[106:109], v[114:117]
	s_waitcnt lgkmcnt(6)
	v_mfma_f32_16x16x32_bf16 v[98:101], v[102:105], v[144:147], v[98:101]
	s_waitcnt lgkmcnt(5)
	v_mfma_f32_16x16x32_bf16 v[102:105], v[178:181], v[106:109], v[170:173]
	s_waitcnt lgkmcnt(4)
	v_mfma_f32_16x16x32_bf16 v[102:105], v[186:189], v[144:147], v[102:105]
	ds_read_b128 v[114:117], v165 offset:48640
	ds_read_b128 v[170:173], v165 offset:48704
	ds_read_b128 v[178:181], v165 offset:50944
	ds_read_b128 v[186:189], v165 offset:51008
	v_pk_mul_f32 v[64:65], v[64:65], v[130:131] op_sel_hi:[1,0]
	v_pk_mul_f32 v[62:63], v[62:63], v[130:131] op_sel_hi:[1,0]
	v_pk_mul_f32 v[68:69], v[68:69], v[130:131] op_sel_hi:[1,0]
	v_pk_mul_f32 v[66:67], v[66:67], v[130:131] op_sel_hi:[1,0]
	s_waitcnt lgkmcnt(7)
	v_mfma_f32_16x16x32_bf16 v[62:65], v[148:151], v[106:109], v[62:65]
	v_mul_f32_e64 v76, v76, v130
	v_mul_f32_e64 v77, v77, v130
	v_pk_mul_f32 v[74:75], v[74:75], v[130:131] op_sel_hi:[1,0]
	v_pk_mul_f32 v[72:73], v[72:73], v[130:131] op_sel_hi:[1,0]
	s_waitcnt lgkmcnt(5)
	v_mfma_f32_16x16x32_bf16 v[66:69], v[174:177], v[106:109], v[66:69]
	v_mul_f32_e64 v70, v70, v130
	v_mul_f32_e64 v71, v71, v130
	v_pk_mul_f32 v[80:81], v[80:81], v[130:131] op_sel_hi:[1,0]
	v_pk_mul_f32 v[78:79], v[78:79], v[130:131] op_sel_hi:[1,0]
	v_mfma_f32_16x16x32_bf16 v[62:65], v[152:155], v[144:147], v[62:65]
	v_mul_f32_e64 v84, v84, v130
	v_mul_f32_e64 v85, v85, v130
	v_pk_mul_f32 v[82:83], v[82:83], v[130:131] op_sel_hi:[1,0]
	v_pk_mul_f32 v[88:89], v[88:89], v[130:131] op_sel_hi:[1,0]
	s_waitcnt lgkmcnt(4)
	v_mfma_f32_16x16x32_bf16 v[66:69], v[182:185], v[144:147], v[66:69]
	ds_read_b128 v[148:151], v165 offset:53248
	ds_read_b128 v[152:155], v165 offset:53312
	ds_read_b128 v[174:177], v165 offset:55552
	ds_read_b128 v[182:185], v165 offset:55616
	v_pk_mul_f32 v[86:87], v[86:87], v[130:131] op_sel_hi:[1,0]
	v_pk_mul_f32 v[92:93], v[92:93], v[130:131] op_sel_hi:[1,0]
	v_pk_mul_f32 v[90:91], v[90:91], v[130:131] op_sel_hi:[1,0]
	s_waitcnt lgkmcnt(7)
	v_mfma_f32_16x16x32_bf16 v[74:77], v[114:117], v[106:109], v[74:77]
	s_waitcnt lgkmcnt(5)
	v_mfma_f32_16x16x32_bf16 v[70:73], v[178:181], v[106:109], v[70:73]
	v_mfma_f32_16x16x32_bf16 v[74:77], v[170:173], v[144:147], v[74:77]
	s_waitcnt lgkmcnt(4)
	v_mfma_f32_16x16x32_bf16 v[70:73], v[186:189], v[144:147], v[70:73]
	ds_read_b128 v[114:117], v165 offset:57856
	ds_read_b128 v[170:173], v165 offset:57920
	ds_read_b128 v[178:181], v165 offset:60160
	ds_read_b128 v[186:189], v165 offset:60224
	s_waitcnt lgkmcnt(7)
	v_mfma_f32_16x16x32_bf16 v[78:81], v[148:151], v[106:109], v[78:81]
	s_waitcnt lgkmcnt(5)
	v_mfma_f32_16x16x32_bf16 v[82:85], v[174:177], v[106:109], v[82:85]
	v_mfma_f32_16x16x32_bf16 v[78:81], v[152:155], v[144:147], v[78:81]
	s_waitcnt lgkmcnt(4)
	v_mfma_f32_16x16x32_bf16 v[82:85], v[182:185], v[144:147], v[82:85]
	ds_write2_b32 v167, v94, v95 offset1:132
	v_add_u32_e32 v94, 0xf800, v166
	ds_write2_b32 v94, v96, v97 offset0:8 offset1:140
	v_add_u32_e32 v94, 0x2000, v167
	ds_write2_b32 v94, v110, v111 offset0:64 offset1:196
	v_add_u32_e32 v94, 0x2400, v167
	ds_write2_b32 v94, v112, v113 offset0:72 offset1:204
	v_add_u32_e32 v94, 0x4200, v167
	ds_write2_b32 v94, v98, v99 offset1:132
	v_add_u32_e32 v94, 0x4600, v167
	ds_write2_b32 v94, v100, v101 offset0:8 offset1:140
	v_add_u32_e32 v94, 0x6200, v167
	ds_write2_b32 v94, v102, v103 offset0:64 offset1:196
	v_add_u32_e32 v94, 0x6600, v167
	ds_write2_b32 v94, v104, v105 offset0:72 offset1:204
	s_waitcnt lgkmcnt(0)
	s_barrier
	ds_read_b128 v[110:113], v168 offset:62464
	ds_read_b128 v[102:105], v168 offset:62480
	ds_read_b128 v[98:101], v168 offset:62496
	ds_read_b128 v[94:97], v168 offset:62512
	s_waitcnt lgkmcnt(14)
	v_mfma_f32_16x16x32_bf16 v[86:89], v[114:117], v[106:109], v[86:89]
	v_lshlrev_b32_e32 v150, 16, v46
	v_lshlrev_b32_e32 v151, 16, v47
	s_mov_b32 s30, 0x5f901000
	s_waitcnt lgkmcnt(13)
	v_mfma_f32_16x16x32_bf16 v[90:93], v[178:181], v[106:109], v[90:93]
	s_waitcnt lgkmcnt(3)
	v_pk_mul_f32 v[106:107], v[112:113], v[112:113]
	v_pk_mul_f32 v[108:109], v[110:111], v[110:111]
	s_nop 0
	v_pk_mov_b32 v[114:115], v[108:109], v[106:107] op_sel:[1,0]
	v_mov_b32_e32 v109, v107
	v_pk_add_f32 v[106:107], v[114:115], v[108:109]
	s_waitcnt lgkmcnt(2)
	v_pk_mul_f32 v[108:109], v[104:105], v[104:105]
	v_pk_mul_f32 v[114:115], v[102:103], v[102:103]
	v_pk_add_f32 v[106:107], v[106:107], v[106:107] op_sel:[0,1] op_sel_hi:[1,0]
	v_pk_mov_b32 v[116:117], v[114:115], v[108:109] op_sel:[1,0]
	v_mov_b32_e32 v115, v109
	v_pk_add_f32 v[108:109], v[116:117], v[114:115]
	s_waitcnt lgkmcnt(0)
	v_mul_f32_e32 v114, v94, v94
	v_mul_f32_e32 v115, v95, v95
	v_pk_add_f32 v[108:109], v[108:109], v[108:109] op_sel:[0,1] op_sel_hi:[1,0]
	v_mov_b32_e32 v107, v114
	v_mov_b32_e32 v109, v115
	v_pk_add_f32 v[106:107], v[106:107], v[108:109]
	v_mul_f32_e32 v108, v99, v99
	v_mul_f32_e32 v114, v101, v101
	v_mul_f32_e32 v116, v96, v96
	v_mul_f32_e32 v117, v97, v97
	v_pk_fma_f32 v[108:109], v[98:99], v[98:99], v[108:109] op_sel_hi:[1,1,0]
	v_pk_fma_f32 v[114:115], v[100:101], v[100:101], v[114:115] op_sel_hi:[1,1,0]
	v_mov_b32_e32 v109, v116
	v_mov_b32_e32 v115, v117
	v_pk_add_f32 v[108:109], v[108:109], v[114:115]
	v_mfma_f32_16x16x32_bf16 v[86:89], v[170:173], v[144:147], v[86:89]
	v_add_f32_e64 v106, v106, v108
	v_add_f32_e64 v107, v107, v109
	v_and_b32_e32 v108, 64, v235
	v_add_f32_e32 v106, v106, v107
	v_xor_b32_e32 v107, 1, v235
	v_add_u32_e32 v108, 64, v108
	v_cmp_lt_i32_e32 vcc, v107, v108
	v_mfma_f32_16x16x32_bf16 v[90:93], v[186:189], v[144:147], v[90:93]
	v_and_b32_e32 v146, 0xffff0000, v46
	v_cndmask_b32_e32 v107, v235, v107, vcc
	v_lshlrev_b32_e32 v107, 2, v107
	ds_bpermute_b32 v107, v107, v106
	v_and_b32_e32 v147, 0xffff0000, v47
	v_lshl_add_u64 v[144:145], v[134:135], 0, s[6:7]
	s_waitcnt lgkmcnt(0)
	v_add_f32_e32 v106, v106, v107
	v_xor_b32_e32 v107, 2, v235
	v_cmp_lt_i32_e32 vcc, v107, v108
	s_nop 1
	v_cndmask_b32_e32 v107, v235, v107, vcc
	v_lshlrev_b32_e32 v107, 2, v107
	ds_bpermute_b32 v107, v107, v106
	s_waitcnt lgkmcnt(0)
	v_add_f32_e32 v106, v106, v107
	v_xor_b32_e32 v107, 4, v235
	v_cmp_lt_i32_e32 vcc, v107, v108
	s_nop 1
	v_cndmask_b32_e32 v107, v235, v107, vcc
	v_lshlrev_b32_e32 v107, 2, v107
	ds_bpermute_b32 v107, v107, v106
	s_waitcnt lgkmcnt(0)
	v_add_f32_e32 v106, v106, v107
	v_fmamk_f32 v106, v106, 0x3c000000, v1
	v_cmp_gt_f32_e32 vcc, s0, v106
	v_mul_f32_e32 v107, 0x4b800000, v106
	s_nop 0
	v_cndmask_b32_e32 v106, v106, v107, vcc
	v_rsq_f32_e32 v106, v106
	s_nop 0
	v_mul_f32_e32 v107, 0x45800000, v106
	v_cndmask_b32_e32 v142, v106, v107, vcc
	v_mul_f32_e32 v106, 0xbfb8aa3b, v150
	v_exp_f32_e32 v106, v106
	v_mov_b32_e32 v107, v112
	v_mov_b32_e32 v112, v111
	v_add_f32_e32 v106, 1.0, v106
	v_rcp_f32_e32 v152, v106
	v_mul_f32_e32 v106, 0xbfb8aa3b, v146
	v_exp_f32_e32 v106, v106
	s_nop 0
	v_add_f32_e32 v106, 1.0, v106
	v_rcp_f32_e32 v148, v106
	v_mov_b32_e32 v106, v110
	v_pk_mul_f32 v[154:155], v[106:107], v[142:143] op_sel_hi:[1,0]
	v_mov_b32_e32 v106, v246
	v_mov_b32_e32 v107, v247
	v_mov_b32_e32 v108, v248
	v_mov_b32_e32 v109, v249
	v_mov_b32_e32 v114, v242
	v_mov_b32_e32 v115, v243
	v_mov_b32_e32 v116, v244
	v_mov_b32_e32 v117, v245
	v_mul_f32_e32 v110, 0xbfb8aa3b, v151
	v_exp_f32_e32 v110, v110
	v_mov_b32_e32 v171, v116
	v_add_f32_e32 v110, 1.0, v110
	v_rcp_f32_e32 v153, v110
	v_pk_mul_f32 v[110:111], v[112:113], v[142:143] op_sel_hi:[1,0]
	v_mul_f32_e32 v112, 0xbfb8aa3b, v147
	v_exp_f32_e32 v112, v112
	v_mov_b32_e32 v116, v115
	v_pk_mul_f32 v[110:111], v[116:117], v[110:111]
	v_mov_b32_e32 v170, v114
	v_add_f32_e32 v112, 1.0, v112
	v_rcp_f32_e32 v149, v112
	v_and_b32_e32 v114, 0xffff0000, v48
	v_mul_f32_e32 v117, 0xbfb8aa3b, v114
	v_exp_f32_e32 v117, v117
	v_pk_mul_f32 v[112:113], v[148:149], v[146:147]
	v_mov_b32_e32 v148, v102
	v_pk_mul_f32 v[110:111], v[112:113], v[110:111]
	v_lshlrev_b32_e32 v113, 16, v49
	v_mul_f32_e32 v102, 0xbfb8aa3b, v113
	v_exp_f32_e32 v102, v102
	v_and_b32_e32 v115, 0xffff0000, v49
	v_add_f32_e32 v117, 1.0, v117
	v_mov_b32_e32 v149, v104
	v_add_f32_e32 v102, 1.0, v102
	v_mov_b32_e32 v104, v103
	v_lshlrev_b32_e32 v112, 16, v48
	v_rcp_f32_e32 v146, v117
	v_rcp_f32_e32 v117, v102
	v_pk_mul_f32 v[102:103], v[104:105], v[142:143] op_sel_hi:[1,0]
	v_mul_f32_e32 v104, 0xbfb8aa3b, v115
	v_mul_f32_e32 v116, 0xbfb8aa3b, v112
	v_exp_f32_e32 v104, v104
	v_exp_f32_e32 v116, v116
	v_pk_mul_f32 v[150:151], v[152:153], v[150:151]
	v_mov_b32_e32 v153, v108
	v_add_f32_e32 v104, 1.0, v104
	v_add_f32_e32 v116, 1.0, v116
	v_rcp_f32_e32 v147, v104
	v_rcp_f32_e32 v116, v116
	v_mov_b32_e32 v108, v107
	v_pk_mul_f32 v[148:149], v[148:149], v[142:143] op_sel_hi:[1,0]
	v_mov_b32_e32 v152, v106
	v_pk_mul_f32 v[102:103], v[108:109], v[102:103]
	v_pk_mul_f32 v[104:105], v[146:147], v[114:115]
	v_pk_mul_f32 v[154:155], v[170:171], v[154:155]
	v_pk_mul_f32 v[148:149], v[152:153], v[148:149]
	v_pk_mul_f32 v[112:113], v[116:117], v[112:113]
	v_pk_mul_f32 v[102:103], v[104:105], v[102:103]
	v_pk_mul_f32 v[150:151], v[150:151], v[154:155]
	v_pk_mul_f32 v[112:113], v[112:113], v[148:149]
	v_bfe_u32 v105, v102, 16, 1
	v_bfe_u32 v104, v103, 16, 1
	v_add3_u32 v102, v102, v105, s33
	v_bfe_u32 v105, v151, 16, 1
	v_bfe_u32 v109, v113, 16, 1
	v_bfe_u32 v106, v111, 16, 1
	v_add3_u32 v103, v103, v104, s33
	v_bfe_u32 v104, v150, 16, 1
	v_bfe_u32 v108, v112, 16, 1
	v_add3_u32 v109, v113, v109, s33
	v_add3_u32 v105, v151, v105, s33
	v_bfe_u32 v107, v110, 16, 1
	v_add3_u32 v106, v111, v106, s33
	v_add3_u32 v108, v112, v108, s33
	v_add3_u32 v104, v150, v104, s33
	v_lshrrev_b32_e32 v111, 16, v105
	v_lshrrev_b32_e32 v105, 16, v109
	v_add3_u32 v107, v110, v107, s33
	v_lshrrev_b32_e32 v110, 16, v104
	v_lshrrev_b32_e32 v104, 16, v108
	v_and_or_b32 v105, v103, s21, v105
	v_and_or_b32 v103, v106, s21, v111
	v_add_co_u32_e32 v106, vcc, s30, v144
	v_and_or_b32 v104, v102, s21, v104
	v_and_or_b32 v102, v107, s21, v110
	v_addc_co_u32_e32 v107, vcc, 0, v145, vcc
	v_lshlrev_b32_e32 v114, 16, v50
	global_store_dwordx4 v[106:107], v[102:105], off offset:1024
	v_and_b32_e32 v108, 0xffff0000, v50
	v_lshlrev_b32_e32 v115, 16, v51
	v_mul_f32_e32 v102, 0xbfb8aa3b, v114
	v_exp_f32_e32 v102, v102
	v_mov_b32_e32 v103, v100
	v_and_b32_e32 v109, 0xffff0000, v51
	v_mov_b32_e32 v100, v99
	v_add_f32_e32 v102, 1.0, v102
	v_rcp_f32_e32 v116, v102
	v_mul_f32_e32 v102, 0xbfb8aa3b, v108
	v_exp_f32_e32 v102, v102
	s_andn2_b64 vcc, exec, s[8:9]
	v_add_f32_e32 v102, 1.0, v102
	v_rcp_f32_e32 v144, v102
	v_mov_b32_e32 v102, v98
	v_pk_mul_f32 v[146:147], v[102:103], v[142:143] op_sel_hi:[1,0]
	v_mov_b32_e32 v102, v230
	v_mov_b32_e32 v103, v234
	v_mov_b32_e32 v104, v236
	v_mov_b32_e32 v105, v238
	v_mov_b32_e32 v110, v250
	v_mov_b32_e32 v111, v251
	v_mov_b32_e32 v112, v241
	v_mov_b32_e32 v113, v228
	v_mul_f32_e32 v98, 0xbfb8aa3b, v115
	v_exp_f32_e32 v98, v98
	v_mov_b32_e32 v149, v112
	v_add_f32_e32 v98, 1.0, v98
	v_rcp_f32_e32 v117, v98
	v_pk_mul_f32 v[98:99], v[100:101], v[142:143] op_sel_hi:[1,0]
	v_mul_f32_e32 v100, 0xbfb8aa3b, v109
	v_exp_f32_e32 v100, v100
	v_mov_b32_e32 v112, v111
	v_pk_mul_f32 v[98:99], v[112:113], v[98:99]
	v_pk_mul_f32 v[114:115], v[116:117], v[114:115]
	v_add_f32_e32 v100, 1.0, v100
	v_rcp_f32_e32 v145, v100
	v_mov_b32_e32 v116, v94
	v_mov_b32_e32 v117, v96
	v_mov_b32_e32 v96, v95
	v_pk_mul_f32 v[100:101], v[144:145], v[108:109]
	v_and_b32_e32 v108, 0xffff0000, v52
	v_pk_mul_f32 v[98:99], v[100:101], v[98:99]
	v_lshlrev_b32_e32 v101, 16, v53
	v_mul_f32_e32 v111, 0xbfb8aa3b, v108
	v_mul_f32_e32 v94, 0xbfb8aa3b, v101
	v_exp_f32_e32 v111, v111
	v_exp_f32_e32 v94, v94
	v_and_b32_e32 v109, 0xffff0000, v53
	v_lshlrev_b32_e32 v100, 16, v52
	v_add_f32_e32 v111, 1.0, v111
	v_add_f32_e32 v94, 1.0, v94
	v_rcp_f32_e32 v112, v111
	v_rcp_f32_e32 v111, v94
	v_pk_mul_f32 v[94:95], v[96:97], v[142:143] op_sel_hi:[1,0]
	v_mul_f32_e32 v96, 0xbfb8aa3b, v109
	v_mov_b32_e32 v148, v110
	v_mul_f32_e32 v110, 0xbfb8aa3b, v100
	v_exp_f32_e32 v96, v96
	v_exp_f32_e32 v110, v110
	v_mov_b32_e32 v145, v104
	v_mov_b32_e32 v104, v103
	v_add_f32_e32 v96, 1.0, v96
	v_add_f32_e32 v110, 1.0, v110
	v_rcp_f32_e32 v113, v96
	v_rcp_f32_e32 v110, v110
	v_pk_mul_f32 v[116:117], v[116:117], v[142:143] op_sel_hi:[1,0]
	v_mov_b32_e32 v144, v102
	v_pk_mul_f32 v[94:95], v[94:95], v[104:105]
	v_pk_mul_f32 v[96:97], v[112:113], v[108:109]
	v_pk_mul_f32 v[146:147], v[148:149], v[146:147]
	v_pk_mul_f32 v[116:117], v[116:117], v[144:145]
	v_pk_mul_f32 v[100:101], v[110:111], v[100:101]
	v_pk_mul_f32 v[94:95], v[96:97], v[94:95]
	v_pk_mul_f32 v[114:115], v[114:115], v[146:147]
	v_pk_mul_f32 v[100:101], v[100:101], v[116:117]
	v_bfe_u32 v96, v95, 16, 1
	v_bfe_u32 v97, v94, 16, 1
	v_bfe_u32 v102, v99, 16, 1
	v_bfe_u32 v103, v98, 16, 1
	v_add3_u32 v98, v98, v103, s33
	v_add3_u32 v99, v99, v102, s33
	v_add3_u32 v94, v94, v97, s33
	v_add3_u32 v95, v95, v96, s33
	v_bfe_u32 v96, v114, 16, 1
	v_bfe_u32 v97, v115, 16, 1
	v_bfe_u32 v102, v100, 16, 1
	v_bfe_u32 v103, v101, 16, 1
	v_add3_u32 v101, v101, v103, s33
	v_add3_u32 v100, v100, v102, s33
	v_add3_u32 v97, v115, v97, s33
	v_add3_u32 v96, v114, v96, s33
	v_lshrrev_b32_e32 v102, 16, v96
	v_lshrrev_b32_e32 v103, 16, v97
	v_lshrrev_b32_e32 v96, 16, v100
	v_lshrrev_b32_e32 v97, 16, v101
	v_and_or_b32 v97, v95, s21, v97
	v_and_or_b32 v96, v94, s21, v96
	v_and_or_b32 v95, v99, s21, v103
	v_and_or_b32 v94, v98, s21, v102
	global_store_dwordx4 v[106:107], v[94:97], off offset:1040
	s_cbranch_vccnz .LBB0_444
	s_waitcnt vmcnt(2)
	v_mov_b64_e32 v[46:47], v[58:59]
	v_mov_b64_e32 v[50:51], v[54:55]
	v_mov_b64_e32 v[48:49], v[60:61]
	v_mov_b64_e32 v[52:53], v[56:57]
	v_mov_b32_e32 v130, v162
	ds_write_b128 v119, v[2:5]
	ds_write_b128 v156, v[6:9]
	ds_write_b128 v119, v[10:13] offset:17408
	ds_write_b128 v156, v[14:17] offset:17408
	ds_write_b128 v143, v[18:21] offset:34816
	ds_write_b128 v143, v[22:25] offset:44032
	ds_write_b128 v157, v[26:29] offset:44032
	ds_write_b128 v158, v[30:33]
	ds_write_b128 v159, v[34:37]
	ds_write_b128 v160, v[38:41]
	ds_write_b128 v161, v[42:45]
	s_branch .LBB0_444
